# grid barrier: the per-CU L1 invalidate is issued by wave 1 of each block between the two block barriers, overlapping the leader's arrival/wait protocol
# baseline (speedup 1.0000x reference)
.LBB0_456:
	v_readlane_b32 s25, v255, 43
	v_readlane_b32 s0, v251, 3
	s_add_i32 s24, s25, 1
	v_readlane_b32 s1, v251, 4
	v_readlane_b32 s48, v255, 11
	v_readlane_b32 s50, v255, 13
	v_readlane_b32 s52, v255, 15
	v_readlane_b32 s54, v255, 17
	v_readlane_b32 s56, v255, 19
	v_readlane_b32 s58, v255, 21
	v_readlane_b32 s60, v255, 23
	s_cmp_ge_i32 s24, s1
	s_mov_b64 s[0:1], -1
	v_readlane_b32 s42, v255, 9
	v_readlane_b32 s49, v255, 12
	v_readlane_b32 s51, v255, 14
	v_readlane_b32 s53, v255, 16
	v_readlane_b32 s55, v255, 18
	v_readlane_b32 s57, v255, 20
	v_readlane_b32 s59, v255, 22
	v_readlane_b32 s61, v255, 24
	v_readlane_b32 s43, v255, 10
	s_cbranch_scc1 .LBB0_8
	v_readlane_b32 s0, v251, 3
	v_readlane_b32 s1, v251, 4
	s_cmp_lg_u32 s25, s0
	s_mov_b64 s[0:1], -1
	s_cbranch_scc0 .LBB0_511
	s_waitcnt vmcnt(0)
	v_mov_b32_e32 v0, v208
	s_waitcnt vmcnt(0) lgkmcnt(0)
	s_barrier
	v_readfirstlane_b32 s25, v0
	s_nop 3
	s_cmp_eq_u32 s25, 64
	s_cbranch_scc0 .Lxb_noinv
	buffer_inv sc1
.Lxb_noinv:
	s_nop 0
	v_cmp_eq_u32_e32 vcc, 0, v0
	s_and_saveexec_b64 s[0:1], vcc
	s_cbranch_execz .LBB0_510
	s_mov_b64 s[26:27], src_shared_base
	v_mov_b32_e32 v131, s27
	s_waitcnt vmcnt(0) expcnt(0) lgkmcnt(0)
	v_readlane_b32 s25, v255, 61
	v_readlane_b32 s26, v255, 62
	v_mov_b32_e32 v133, s27
	s_nop 0
	v_mov_b32_e32 v2, s25
	v_mov_b32_e32 v0, s26
	s_nop 0
	v_cmp_eq_u32_e32 vcc, 0, v2
	s_and_saveexec_b64 s[30:31], vcc
	s_cbranch_execz .LBB0_474
	s_mov_b32 s25, 1
	s_mov_b32 s27, s22
	s_branch .LBB0_462

.LBB0_510:
	s_or_b64 exec, exec, s[0:1]
	s_mov_b64 s[0:1], 0
	s_mov_b32 s26, s22
	s_waitcnt vmcnt(0) lgkmcnt(0)
	s_barrier
